# P3 delta items segment (c): per-row decay/beta quads read once with two ds_read_b128 instead of 32 serialized ds_read_b32
# speedup vs baseline: 1.0027x; 1.0027x over previous
.LBB0_333:
	s_waitcnt lgkmcnt(0)
	s_barrier
	ds_read_b128 v[2:5], v148 offset:34816
	ds_read_b128 v[6:9], v148 offset:35328
	ds_read_b128 v[34:37], v213
	ds_read_b128 v[38:41], v213 offset:17408
	ds_read_b128 v[42:45], v214
	ds_read_b128 v[50:53], v214 offset:4352
	ds_read_b128 v[58:61], v214 offset:8704
	ds_read_b128 v[66:69], v214 offset:13056
	s_waitcnt lgkmcnt(3)
	v_mfma_f32_16x16x32_bf16 v[46:49], v[34:37], v[42:45], 0
	v_readlane_b32 s2, v250, 14
	v_readlane_b32 s3, v250, 15
	v_mfma_f32_16x16x32_bf16 v[42:45], v[38:41], v[42:45], 0
	s_waitcnt lgkmcnt(2)
	v_mfma_f32_16x16x32_bf16 v[54:57], v[34:37], v[50:53], 0
	v_mfma_f32_16x16x32_bf16 v[50:53], v[38:41], v[50:53], 0
	s_waitcnt lgkmcnt(1)
	v_mfma_f32_16x16x32_bf16 v[62:65], v[34:37], v[58:61], 0
	v_mfma_f32_16x16x32_bf16 v[58:61], v[38:41], v[58:61], 0
	s_waitcnt lgkmcnt(0)
	v_mfma_f32_16x16x32_bf16 v[34:37], v[34:37], v[66:69], 0
	v_mfma_f32_16x16x32_bf16 v[38:41], v[38:41], v[66:69], 0
	ds_read_b128 v[66:69], v213 offset:64
	ds_read_b128 v[96:99], v213 offset:17472
	ds_read_b128 v[100:103], v214 offset:64
	s_waitcnt lgkmcnt(0)
	v_mfma_f32_16x16x32_bf16 v[46:49], v[66:69], v[100:103], v[46:49]
	v_mfma_f32_16x16x32_bf16 v[42:45], v[96:99], v[100:103], v[42:45]
	ds_read_b128 v[100:103], v214 offset:4416
	s_waitcnt lgkmcnt(0)
	v_mfma_f32_16x16x32_bf16 v[54:57], v[66:69], v[100:103], v[54:57]
	v_mfma_f32_16x16x32_bf16 v[50:53], v[96:99], v[100:103], v[50:53]
	ds_read_b128 v[100:103], v214 offset:8768
	s_waitcnt lgkmcnt(0)
	v_mfma_f32_16x16x32_bf16 v[62:65], v[66:69], v[100:103], v[62:65]
	v_mfma_f32_16x16x32_bf16 v[58:61], v[96:99], v[100:103], v[58:61]
	ds_read_b128 v[100:103], v214 offset:13120
	s_waitcnt lgkmcnt(0)
	v_mfma_f32_16x16x32_bf16 v[34:37], v[66:69], v[100:103], v[34:37]
	v_mfma_f32_16x16x32_bf16 v[38:41], v[96:99], v[100:103], v[38:41]
	ds_read_b128 v[66:69], v213 offset:128
	ds_read_b128 v[96:99], v213 offset:17536
	ds_read_b128 v[100:103], v214 offset:128
	s_waitcnt lgkmcnt(0)
	v_mfma_f32_16x16x32_bf16 v[46:49], v[66:69], v[100:103], v[46:49]
	v_mfma_f32_16x16x32_bf16 v[42:45], v[96:99], v[100:103], v[42:45]
	ds_read_b128 v[100:103], v214 offset:4480
	s_waitcnt lgkmcnt(0)
	v_mfma_f32_16x16x32_bf16 v[54:57], v[66:69], v[100:103], v[54:57]
	v_mfma_f32_16x16x32_bf16 v[50:53], v[96:99], v[100:103], v[50:53]
	ds_read_b128 v[100:103], v214 offset:8832
	s_waitcnt lgkmcnt(0)
	v_mfma_f32_16x16x32_bf16 v[104:107], v[66:69], v[100:103], v[62:65]
	v_mfma_f32_16x16x32_bf16 v[100:103], v[96:99], v[100:103], v[58:61]
	s_nop 2
	ds_read_b128 v[58:61], v214 offset:13184
	s_waitcnt lgkmcnt(0)
	v_mfma_f32_16x16x32_bf16 v[34:37], v[66:69], v[58:61], v[34:37]
	v_mfma_f32_16x16x32_bf16 v[66:69], v[96:99], v[58:61], v[38:41]
	s_nop 2
	ds_read_b128 v[38:41], v213 offset:192
	ds_read_b128 v[96:99], v213 offset:17600
	ds_read_b128 v[58:61], v214 offset:192
	s_waitcnt lgkmcnt(0)
	v_mfma_f32_16x16x32_bf16 v[62:65], v[38:41], v[58:61], v[46:49]
	v_mfma_f32_16x16x32_bf16 v[58:61], v[96:99], v[58:61], v[42:45]
	s_nop 2
	ds_read_b128 v[42:45], v214 offset:4544
	s_waitcnt lgkmcnt(0)
	v_mfma_f32_16x16x32_bf16 v[54:57], v[38:41], v[42:45], v[54:57]
	v_mfma_f32_16x16x32_bf16 v[50:53], v[96:99], v[42:45], v[50:53]
	ds_read_b128 v[42:45], v214 offset:8896
	s_waitcnt lgkmcnt(0)
	v_mfma_f32_16x16x32_bf16 v[46:49], v[38:41], v[42:45], v[104:107]
	v_mfma_f32_16x16x32_bf16 v[42:45], v[96:99], v[42:45], v[100:103]
	s_nop 2
	ds_read_b128 v[100:103], v214 offset:13248
	s_waitcnt lgkmcnt(0)
	v_mfma_f32_16x16x32_bf16 v[38:41], v[38:41], v[100:103], v[34:37]
	v_mfma_f32_16x16x32_bf16 v[34:37], v[96:99], v[100:103], v[66:69]
	ds_read2st64_b32 v[96:97], v147 offset0:136 offset1:138
	s_nop 1
	v_mov_b32_e32 v66, v2
	v_cndmask_b32_e64 v68, 0, 1, s[2:3]
	v_cmp_ne_u32_e64 s[68:69], 1, v68
	s_waitcnt lgkmcnt(0)
	v_sub_f32_e32 v66, v66, v96
	v_mul_f32_e64 v66, |v66|, s51
	v_exp_f32_e32 v67, v66
	v_mov_b32_e32 v66, 0
	s_and_saveexec_b64 s[2:3], s[4:5]
	s_cbranch_execz .LBB0_337
	s_and_b64 vcc, exec, s[68:69]
	v_mov_b32_e32 v66, v97
	s_cbranch_vccnz .LBB0_336
	v_mov_b32_e32 v66, v6

.LBB0_337:
	s_or_b64 exec, exec, s[2:3]
	s_mov_b64 s[2:3], exec
	v_readlane_b32 s88, v250, 16
	v_readlane_b32 s89, v250, 17
	s_and_b64 s[88:89], s[2:3], s[88:89]
	s_mov_b64 exec, s[88:89]
	v_mul_f32_e32 v58, v58, v67
	v_cvt_pk_bf16_f32 v58, v58, s0
	v_add_u32_e32 v62, v149, v150
	ds_write_b16 v62, v58
	s_or_b64 exec, exec, s[2:3]
	v_mov_b32_e32 v58, v3
	v_mov_b32_e32 v67, 0
	s_waitcnt lgkmcnt(0)
	v_sub_f32_e32 v58, v58, v96
	v_mul_f32_e64 v58, |v58|, s51
	v_exp_f32_e32 v58, v58
	s_and_saveexec_b64 s[2:3], s[6:7]
	s_cbranch_execz .LBB0_343
	s_and_b64 vcc, exec, s[68:69]
	v_mov_b32_e32 v62, v97
	s_cbranch_vccnz .LBB0_342
	v_mov_b32_e32 v62, v7

.LBB0_343:
	s_or_b64 exec, exec, s[2:3]
	s_mov_b64 s[2:3], exec
	v_readlane_b32 s88, v250, 18
	v_readlane_b32 s89, v250, 19
	s_and_b64 s[88:89], s[2:3], s[88:89]
	s_mov_b64 exec, s[88:89]
	v_mul_f32_e32 v58, v59, v58
	v_cvt_pk_bf16_f32 v58, v58, s0
	v_add_u32_e32 v59, v149, v151
	ds_write_b16 v59, v58
	s_or_b64 exec, exec, s[2:3]
	v_mov_b32_e32 v58, v4
	v_mov_b32_e32 v68, 0
	s_waitcnt lgkmcnt(0)
	v_sub_f32_e32 v58, v58, v96
	v_mul_f32_e64 v58, |v58|, s51
	v_exp_f32_e32 v58, v58
	s_and_saveexec_b64 s[2:3], s[8:9]
	s_cbranch_execz .LBB0_349
	s_and_b64 vcc, exec, s[68:69]
	v_mov_b32_e32 v59, v97
	s_cbranch_vccnz .LBB0_348
	v_mov_b32_e32 v59, v8

.LBB0_349:
	s_or_b64 exec, exec, s[2:3]
	s_mov_b64 s[2:3], exec
	v_readlane_b32 s88, v250, 20
	v_readlane_b32 s89, v250, 21
	s_and_b64 s[88:89], s[2:3], s[88:89]
	s_mov_b64 exec, s[88:89]
	v_mul_f32_e32 v58, v60, v58
	v_cvt_pk_bf16_f32 v58, v58, s0
	v_add_u32_e32 v59, v149, v152
	ds_write_b16 v59, v58
	s_or_b64 exec, exec, s[2:3]
	v_mov_b32_e32 v58, v5
	v_mov_b32_e32 v69, 0
	s_waitcnt lgkmcnt(0)
	v_sub_f32_e32 v58, v58, v96
	v_mul_f32_e64 v58, |v58|, s51
	v_exp_f32_e32 v58, v58
	s_and_saveexec_b64 s[2:3], s[10:11]
	s_cbranch_execz .LBB0_355
	s_and_b64 vcc, exec, s[68:69]
	s_cbranch_vccnz .LBB0_354
	v_mov_b32_e32 v97, v9

.LBB0_359:
	v_add_u32_e32 v58, 64, v147
	ds_read2st64_b32 v[62:63], v58 offset0:136 offset1:138
	v_mov_b32_e32 v58, v2
	s_waitcnt lgkmcnt(0)
	v_sub_f32_e32 v58, v58, v62
	v_mul_f32_e64 v58, |v58|, s51
	v_exp_f32_e32 v59, v58
	v_mov_b32_e32 v58, 0
	s_and_saveexec_b64 s[2:3], s[12:13]
	s_cbranch_execz .LBB0_363
	s_and_b64 vcc, exec, s[68:69]
	v_mov_b32_e32 v58, v63
	s_cbranch_vccnz .LBB0_362
	v_mov_b32_e32 v58, v6

.LBB0_363:
	s_or_b64 exec, exec, s[2:3]
	s_mov_b64 s[2:3], exec
	v_readlane_b32 s88, v250, 24
	v_readlane_b32 s89, v250, 25
	s_and_b64 s[88:89], s[2:3], s[88:89]
	s_mov_b64 exec, s[88:89]
	v_mul_f32_e32 v50, v50, v59
	v_cvt_pk_bf16_f32 v50, v50, s0
	ds_write_b16 v186, v50
	s_or_b64 exec, exec, s[2:3]
	v_mov_b32_e32 v50, v3
	v_mov_b32_e32 v59, 0
	s_waitcnt lgkmcnt(0)
	v_sub_f32_e32 v50, v50, v62
	v_mul_f32_e64 v50, |v50|, s51
	v_exp_f32_e32 v50, v50
	s_and_saveexec_b64 s[2:3], s[14:15]
	s_cbranch_execz .LBB0_369
	s_and_b64 vcc, exec, s[68:69]
	v_mov_b32_e32 v54, v63
	s_cbranch_vccnz .LBB0_368
	v_mov_b32_e32 v54, v7

.LBB0_369:
	s_or_b64 exec, exec, s[2:3]
	s_mov_b64 s[2:3], exec
	v_readlane_b32 s88, v250, 26
	v_readlane_b32 s89, v250, 27
	s_and_b64 s[88:89], s[2:3], s[88:89]
	s_mov_b64 exec, s[88:89]
	v_mul_f32_e32 v50, v51, v50
	v_cvt_pk_bf16_f32 v50, v50, s0
	ds_write_b16 v187, v50
	s_or_b64 exec, exec, s[2:3]
	v_mov_b32_e32 v50, v4
	v_mov_b32_e32 v60, 0
	s_waitcnt lgkmcnt(0)
	v_sub_f32_e32 v50, v50, v62
	v_mul_f32_e64 v50, |v50|, s51
	v_exp_f32_e32 v50, v50
	s_and_saveexec_b64 s[2:3], s[16:17]
	s_cbranch_execz .LBB0_375
	s_and_b64 vcc, exec, s[68:69]
	v_mov_b32_e32 v51, v63
	s_cbranch_vccnz .LBB0_374
	v_mov_b32_e32 v51, v8

.LBB0_375:
	s_or_b64 exec, exec, s[2:3]
	s_mov_b64 s[2:3], exec
	v_readlane_b32 s88, v250, 28
	v_readlane_b32 s89, v250, 29
	s_and_b64 s[88:89], s[2:3], s[88:89]
	s_mov_b64 exec, s[88:89]
	v_mul_f32_e32 v50, v52, v50
	v_cvt_pk_bf16_f32 v50, v50, s0
	ds_write_b16 v188, v50
	s_or_b64 exec, exec, s[2:3]
	v_mov_b32_e32 v50, v5
	v_mov_b32_e32 v61, 0
	s_waitcnt lgkmcnt(0)
	v_sub_f32_e32 v50, v50, v62
	v_mul_f32_e64 v50, |v50|, s51
	v_exp_f32_e32 v50, v50
	s_and_saveexec_b64 s[2:3], s[18:19]
	s_cbranch_execz .LBB0_381
	s_and_b64 vcc, exec, s[68:69]
	s_cbranch_vccnz .LBB0_380
	v_mov_b32_e32 v63, v9

.LBB0_385:
	v_add_u32_e32 v50, 0x80, v147
	ds_read2st64_b32 v[54:55], v50 offset0:136 offset1:138
	v_mov_b32_e32 v50, v2
	s_waitcnt lgkmcnt(0)
	v_sub_f32_e32 v50, v50, v54
	v_mul_f32_e64 v50, |v50|, s51
	v_exp_f32_e32 v51, v50
	v_mov_b32_e32 v50, 0
	s_and_saveexec_b64 s[2:3], s[20:21]
	s_cbranch_execz .LBB0_389
	s_and_b64 vcc, exec, s[68:69]
	v_mov_b32_e32 v50, v55
	s_cbranch_vccnz .LBB0_388
	v_mov_b32_e32 v50, v6

.LBB0_389:
	s_or_b64 exec, exec, s[2:3]
	s_mov_b64 s[2:3], exec
	v_readlane_b32 s88, v250, 34
	v_readlane_b32 s89, v250, 35
	s_and_b64 s[88:89], s[2:3], s[88:89]
	s_mov_b64 exec, s[88:89]
	v_mul_f32_e32 v42, v42, v51
	v_cvt_pk_bf16_f32 v42, v42, s0
	ds_write_b16 v190, v42
	s_or_b64 exec, exec, s[2:3]
	v_mov_b32_e32 v42, v3
	v_mov_b32_e32 v51, 0
	s_waitcnt lgkmcnt(0)
	v_sub_f32_e32 v42, v42, v54
	v_mul_f32_e64 v42, |v42|, s51
	v_exp_f32_e32 v42, v42
	s_and_saveexec_b64 s[2:3], s[22:23]
	s_cbranch_execz .LBB0_395
	s_and_b64 vcc, exec, s[68:69]
	v_mov_b32_e32 v46, v55
	s_cbranch_vccnz .LBB0_394
	v_mov_b32_e32 v46, v7

.LBB0_395:
	s_or_b64 exec, exec, s[2:3]
	s_mov_b64 s[2:3], exec
	v_readlane_b32 s88, v250, 36
	v_readlane_b32 s89, v250, 37
	s_and_b64 s[88:89], s[2:3], s[88:89]
	s_mov_b64 exec, s[88:89]
	v_mul_f32_e32 v42, v43, v42
	v_cvt_pk_bf16_f32 v42, v42, s0
	ds_write_b16 v191, v42
	s_or_b64 exec, exec, s[2:3]
	v_mov_b32_e32 v42, v4
	v_mov_b32_e32 v52, 0
	s_waitcnt lgkmcnt(0)
	v_sub_f32_e32 v42, v42, v54
	v_mul_f32_e64 v42, |v42|, s51
	v_exp_f32_e32 v42, v42
	s_and_saveexec_b64 s[2:3], s[24:25]
	s_cbranch_execz .LBB0_401
	s_and_b64 vcc, exec, s[68:69]
	v_mov_b32_e32 v43, v55
	s_cbranch_vccnz .LBB0_400
	v_mov_b32_e32 v43, v8

.LBB0_401:
	s_or_b64 exec, exec, s[2:3]
	s_and_saveexec_b64 s[2:3], s[56:57]
	v_mul_f32_e32 v42, v44, v42
	v_cvt_pk_bf16_f32 v42, v42, s0
	ds_write_b16 v192, v42
	s_or_b64 exec, exec, s[2:3]
	v_mov_b32_e32 v42, v5
	v_mov_b32_e32 v53, 0
	s_waitcnt lgkmcnt(0)
	v_sub_f32_e32 v42, v42, v54
	v_mul_f32_e64 v42, |v42|, s51
	v_exp_f32_e32 v42, v42
	s_and_saveexec_b64 s[2:3], s[26:27]
	s_cbranch_execz .LBB0_407
	s_and_b64 vcc, exec, s[68:69]
	s_cbranch_vccnz .LBB0_406
	v_mov_b32_e32 v55, v9

.LBB0_411:
	v_add_u32_e32 v42, 0xc0, v147
	ds_read2st64_b32 v[46:47], v42 offset0:136 offset1:138
	v_mov_b32_e32 v42, v2
	s_waitcnt lgkmcnt(0)
	v_sub_f32_e32 v42, v42, v46
	v_mul_f32_e64 v42, |v42|, s51
	v_exp_f32_e32 v43, v42
	v_mov_b32_e32 v42, 0
	s_and_saveexec_b64 s[2:3], s[28:29]
	s_cbranch_execz .LBB0_415
	s_and_b64 vcc, exec, s[68:69]
	v_mov_b32_e32 v42, v47
	s_cbranch_vccnz .LBB0_414
	v_mov_b32_e32 v42, v6

.LBB0_415:
	s_or_b64 exec, exec, s[2:3]
	s_and_saveexec_b64 s[2:3], s[62:63]
	v_mul_f32_e32 v34, v34, v43
	v_cvt_pk_bf16_f32 v34, v34, s0
	ds_write_b16 v194, v34
	s_or_b64 exec, exec, s[2:3]
	v_mov_b32_e32 v34, v3
	v_mov_b32_e32 v43, 0
	s_waitcnt lgkmcnt(0)
	v_sub_f32_e32 v34, v34, v46
	v_mul_f32_e64 v34, |v34|, s51
	v_exp_f32_e32 v34, v34
	s_and_saveexec_b64 s[2:3], s[30:31]
	s_cbranch_execz .LBB0_421
	s_and_b64 vcc, exec, s[68:69]
	v_mov_b32_e32 v38, v47
	s_cbranch_vccnz .LBB0_420
	v_mov_b32_e32 v38, v7

.LBB0_421:
	s_or_b64 exec, exec, s[2:3]
	s_and_saveexec_b64 s[2:3], s[64:65]
	v_mul_f32_e32 v34, v35, v34
	v_cvt_pk_bf16_f32 v34, v34, s0
	ds_write_b16 v195, v34
	s_or_b64 exec, exec, s[2:3]
	v_mov_b32_e32 v34, v4
	v_mov_b32_e32 v44, 0
	s_waitcnt lgkmcnt(0)
	v_sub_f32_e32 v34, v34, v46
	v_mul_f32_e64 v34, |v34|, s51
	v_exp_f32_e32 v34, v34
	s_and_saveexec_b64 s[2:3], s[34:35]
	s_cbranch_execz .LBB0_427
	s_and_b64 vcc, exec, s[68:69]
	v_mov_b32_e32 v35, v47
	s_cbranch_vccnz .LBB0_426
	v_mov_b32_e32 v35, v8

.LBB0_427:
	s_or_b64 exec, exec, s[2:3]
	s_and_saveexec_b64 s[2:3], s[90:91]
	v_mul_f32_e32 v34, v36, v34
	v_cvt_pk_bf16_f32 v34, v34, s0
	ds_write_b16 v196, v34
	s_or_b64 exec, exec, s[2:3]
	v_mov_b32_e32 v34, v5
	v_mov_b32_e32 v45, 0
	s_waitcnt lgkmcnt(0)
	v_sub_f32_e32 v34, v34, v46
	v_mul_f32_e64 v34, |v34|, s51
	v_exp_f32_e32 v34, v34
	s_and_saveexec_b64 s[2:3], s[36:37]
	s_cbranch_execz .LBB0_433
	s_and_b64 vcc, exec, s[68:69]
	s_cbranch_vccnz .LBB0_432
	v_mov_b32_e32 v47, v9
